# stack: v163 + hand-written norm0 (params in registers, prefetch, DPP reductions)
# speedup vs baseline: 1.0027x; 1.0027x over previous
.LBB0_37:
	s_waitcnt lgkmcnt(0)
	v_writelane_b32 v255, s76, 3
	s_lshl_b32 s0, s2, 3
	v_mbcnt_lo_u32_b32 v139, -1, 0
	v_writelane_b32 v255, s77, 4
	v_writelane_b32 v255, s78, 5
	v_writelane_b32 v255, s79, 6
	v_writelane_b32 v255, s80, 7
	v_writelane_b32 v255, s81, 8
	v_writelane_b32 v255, s82, 9
	v_writelane_b32 v255, s83, 10
	v_writelane_b32 v255, s84, 11
	v_writelane_b32 v255, s85, 12
	v_writelane_b32 v255, s86, 13
	v_writelane_b32 v255, s87, 14
	v_writelane_b32 v255, s88, 15
	v_writelane_b32 v255, s89, 16
	v_writelane_b32 v255, s90, 17
	v_writelane_b32 v255, s91, 18
	s_lshl_b32 s82, s33, 3
	v_readlane_b32 s1, v255, 2
	s_add_i32 s26, s1, s0
	s_cmp_lt_i32 s26, 0x8000
	s_cselect_b64 s[0:1], -1, 0
	v_writelane_b32 v255, s0, 19
	s_cmpk_gt_i32 s26, 0x7fff
	s_nop 0
	v_writelane_b32 v255, s1, 20
	s_barrier
	v_mbcnt_lo_u32_b32 v2, -1, 0
	v_mbcnt_hi_u32_b32 v2, -1, v2
	s_cbranch_scc1 .LBB0_42
	s_cmp_lg_u32 s33, 0x100
	s_cbranch_scc1 .Lnorm0_orig
	v_mbcnt_lo_u32_b32 v133, -1, 0
	v_mbcnt_hi_u32_b32 v133, -1, v133
	v_readlane_b32 s44, v255, 11
	v_readlane_b32 s45, v255, 12
	v_readlane_b32 s10, v255, 3
	v_readlane_b32 s11, v255, 4
	v_lshlrev_b32_e32 v134, 3, v133
	v_lshlrev_b32_e32 v133, 4, v133
	v_mov_b32_e32 v135, 0x358637bd
	s_lshr_b32 s1, s26, 9
	s_and_b32 s8, s26, 0x1ff
	s_lshl_b32 s9, s1, 13
	s_add_u32 s9, s9, s8
	s_mul_i32 s6, s1, 0x3000
	s_add_u32 s40, s34, s6
	s_addc_u32 s41, s35, 0
	s_add_u32 s42, s40, 0x1000
	s_addc_u32 s43, s41, 0
	s_lshl_b32 s6, s9, 12
	s_add_u32 s10, s10, s6
	s_addc_u32 s11, s11, 0
	s_add_u32 s12, s10, 0x200000
	s_addc_u32 s13, s11, 0
	s_lshl_b32 s6, s9, 11
	s_add_u32 s36, s60, s6
	s_addc_u32 s37, s61, 0
	s_add_u32 s38, s36, 0x100000
	s_addc_u32 s39, s37, 0
	s_mov_b32 s8, 0
	global_load_dwordx4 v[66:69], v133, s[44:45]
	global_load_dwordx4 v[70:73], v133, s[44:45] offset:1024
	global_load_dwordx4 v[74:77], v133, s[44:45] offset:2048
	global_load_dwordx4 v[78:81], v133, s[44:45] offset:3072
	global_load_dwordx4 v[82:85], v133, s[40:41]
	global_load_dwordx4 v[86:89], v133, s[40:41] offset:1024
	global_load_dwordx4 v[90:93], v133, s[40:41] offset:2048
	global_load_dwordx4 v[94:97], v133, s[40:41] offset:3072
	global_load_dwordx4 v[98:101], v133, s[42:43]
	global_load_dwordx4 v[102:105], v133, s[42:43] offset:1024
	global_load_dwordx4 v[106:109], v133, s[42:43] offset:2048
	global_load_dwordx4 v[110:113], v133, s[42:43] offset:3072
	global_load_dwordx4 v[2:5], v133, s[10:11] nt
	global_load_dwordx4 v[6:9], v133, s[10:11] offset:1024 nt
	global_load_dwordx4 v[10:13], v133, s[10:11] offset:2048 nt
	global_load_dwordx4 v[14:17], v133, s[10:11] offset:3072 nt
	global_load_dwordx4 v[18:21], v133, s[12:13] nt
	global_load_dwordx4 v[22:25], v133, s[12:13] offset:1024 nt
	global_load_dwordx4 v[26:29], v133, s[12:13] offset:2048 nt
	global_load_dwordx4 v[30:33], v133, s[12:13] offset:3072 nt
	s_waitcnt vmcnt(0)
	v_add_f32_e32 v98, 1.0, v98
	v_add_f32_e32 v99, 1.0, v99
	v_add_f32_e32 v100, 1.0, v100
	v_add_f32_e32 v101, 1.0, v101
	v_add_f32_e32 v102, 1.0, v102
	v_add_f32_e32 v103, 1.0, v103
	v_add_f32_e32 v104, 1.0, v104
	v_add_f32_e32 v105, 1.0, v105
	v_add_f32_e32 v106, 1.0, v106
	v_add_f32_e32 v107, 1.0, v107
	v_add_f32_e32 v108, 1.0, v108
	v_add_f32_e32 v109, 1.0, v109
	v_add_f32_e32 v110, 1.0, v110
	v_add_f32_e32 v111, 1.0, v111
	v_add_f32_e32 v112, 1.0, v112
	v_add_f32_e32 v113, 1.0, v113
.Lnorm0_loop:
	s_add_u32 s10, s10, 0x400000
	s_addc_u32 s11, s11, 0
	s_add_u32 s12, s12, 0x400000
	s_addc_u32 s13, s13, 0
	global_load_dwordx4 v[34:37], v133, s[10:11] nt
	global_load_dwordx4 v[38:41], v133, s[10:11] offset:1024 nt
	global_load_dwordx4 v[42:45], v133, s[10:11] offset:2048 nt
	global_load_dwordx4 v[46:49], v133, s[10:11] offset:3072 nt
	global_load_dwordx4 v[50:53], v133, s[12:13] nt
	global_load_dwordx4 v[54:57], v133, s[12:13] offset:1024 nt
	global_load_dwordx4 v[58:61], v133, s[12:13] offset:2048 nt
	global_load_dwordx4 v[62:65], v133, s[12:13] offset:3072 nt
	s_waitcnt vmcnt(20)
	v_mul_f32_e32 v130, v2, v2
	v_fmac_f32_e32 v130, v3, v3
	v_fmac_f32_e32 v130, v4, v4
	v_fmac_f32_e32 v130, v5, v5
	v_fmac_f32_e32 v130, v6, v6
	v_fmac_f32_e32 v130, v7, v7
	v_fmac_f32_e32 v130, v8, v8
	v_fmac_f32_e32 v130, v9, v9
	v_fmac_f32_e32 v130, v10, v10
	v_fmac_f32_e32 v130, v11, v11
	v_fmac_f32_e32 v130, v12, v12
	v_fmac_f32_e32 v130, v13, v13
	v_fmac_f32_e32 v130, v14, v14
	v_fmac_f32_e32 v130, v15, v15
	v_fmac_f32_e32 v130, v16, v16
	v_fmac_f32_e32 v130, v17, v17
	s_nop 1
	v_add_f32_dpp v131, v130, v130 quad_perm:[1,0,3,2] row_mask:0xf bank_mask:0xf
	s_nop 1
	v_add_f32_dpp v130, v131, v131 quad_perm:[2,3,0,1] row_mask:0xf bank_mask:0xf
	s_nop 1
	v_add_f32_dpp v131, v130, v130 row_half_mirror row_mask:0xf bank_mask:0xf
	s_nop 1
	v_add_f32_dpp v130, v131, v131 row_mirror row_mask:0xf bank_mask:0xf
	s_nop 0
	v_readlane_b32 s0, v130, 0
	v_readlane_b32 s1, v130, 16
	v_readlane_b32 s6, v130, 32
	v_readlane_b32 s7, v130, 48
	s_nop 1
	v_mov_b32_e32 v131, s0
	v_add_f32_e32 v131, s1, v131
	v_add_f32_e32 v131, s6, v131
	v_add_f32_e32 v131, s7, v131
	v_fmamk_f32 v131, v131, 0x3a800000, v135
	v_rsq_f32_e32 v132, v131
	s_nop 0
	v_mul_f32_e32 v114, v2, v132
	v_mul_f32_e32 v115, v3, v132
	v_mul_f32_e32 v116, v4, v132
	v_mul_f32_e32 v117, v5, v132
	v_mul_f32_e32 v118, v6, v132
	v_mul_f32_e32 v119, v7, v132
	v_mul_f32_e32 v120, v8, v132
	v_mul_f32_e32 v121, v9, v132
	v_mul_f32_e32 v122, v10, v132
	v_mul_f32_e32 v123, v11, v132
	v_mul_f32_e32 v124, v12, v132
	v_mul_f32_e32 v125, v13, v132
	v_mul_f32_e32 v126, v14, v132
	v_mul_f32_e32 v127, v15, v132
	v_mul_f32_e32 v128, v16, v132
	v_mul_f32_e32 v129, v17, v132
	v_mul_f32_e32 v114, v66, v114
	v_mul_f32_e32 v115, v67, v115
	v_mul_f32_e32 v116, v68, v116
	v_mul_f32_e32 v117, v69, v117
	v_mul_f32_e32 v118, v70, v118
	v_mul_f32_e32 v119, v71, v119
	v_mul_f32_e32 v120, v72, v120
	v_mul_f32_e32 v121, v73, v121
	v_mul_f32_e32 v122, v74, v122
	v_mul_f32_e32 v123, v75, v123
	v_mul_f32_e32 v124, v76, v124
	v_mul_f32_e32 v125, v77, v125
	v_mul_f32_e32 v126, v78, v126
	v_mul_f32_e32 v127, v79, v127
	v_mul_f32_e32 v128, v80, v128
	v_mul_f32_e32 v129, v81, v129
	v_fma_f32 v114, v114, v98, v82
	v_fma_f32 v115, v115, v99, v83
	v_fma_f32 v116, v116, v100, v84
	v_fma_f32 v117, v117, v101, v85
	v_fma_f32 v118, v118, v102, v86
	v_fma_f32 v119, v119, v103, v87
	v_fma_f32 v120, v120, v104, v88
	v_fma_f32 v121, v121, v105, v89
	v_fma_f32 v122, v122, v106, v90
	v_fma_f32 v123, v123, v107, v91
	v_fma_f32 v124, v124, v108, v92
	v_fma_f32 v125, v125, v109, v93
	v_fma_f32 v126, v126, v110, v94
	v_fma_f32 v127, v127, v111, v95
	v_fma_f32 v128, v128, v112, v96
	v_fma_f32 v129, v129, v113, v97
	v_cvt_pk_bf16_f32 v114, v114, v115
	v_cvt_pk_bf16_f32 v115, v116, v117
	v_cvt_pk_bf16_f32 v116, v118, v119
	v_cvt_pk_bf16_f32 v117, v120, v121
	v_cvt_pk_bf16_f32 v118, v122, v123
	v_cvt_pk_bf16_f32 v119, v124, v125
	v_cvt_pk_bf16_f32 v120, v126, v127
	v_cvt_pk_bf16_f32 v121, v128, v129
	global_store_dwordx2 v134, v[114:115], s[36:37]
	global_store_dwordx2 v134, v[116:117], s[36:37] offset:512
	global_store_dwordx2 v134, v[118:119], s[36:37] offset:1024
	global_store_dwordx2 v134, v[120:121], s[36:37] offset:1536
	s_waitcnt vmcnt(12)
	v_mul_f32_e32 v130, v18, v18
	v_fmac_f32_e32 v130, v19, v19
	v_fmac_f32_e32 v130, v20, v20
	v_fmac_f32_e32 v130, v21, v21
	v_fmac_f32_e32 v130, v22, v22
	v_fmac_f32_e32 v130, v23, v23
	v_fmac_f32_e32 v130, v24, v24
	v_fmac_f32_e32 v130, v25, v25
	v_fmac_f32_e32 v130, v26, v26
	v_fmac_f32_e32 v130, v27, v27
	v_fmac_f32_e32 v130, v28, v28
	v_fmac_f32_e32 v130, v29, v29
	v_fmac_f32_e32 v130, v30, v30
	v_fmac_f32_e32 v130, v31, v31
	v_fmac_f32_e32 v130, v32, v32
	v_fmac_f32_e32 v130, v33, v33
	s_nop 1
	v_add_f32_dpp v131, v130, v130 quad_perm:[1,0,3,2] row_mask:0xf bank_mask:0xf
	s_nop 1
	v_add_f32_dpp v130, v131, v131 quad_perm:[2,3,0,1] row_mask:0xf bank_mask:0xf
	s_nop 1
	v_add_f32_dpp v131, v130, v130 row_half_mirror row_mask:0xf bank_mask:0xf
	s_nop 1
	v_add_f32_dpp v130, v131, v131 row_mirror row_mask:0xf bank_mask:0xf
	s_nop 0
	v_readlane_b32 s0, v130, 0
	v_readlane_b32 s1, v130, 16
	v_readlane_b32 s6, v130, 32
	v_readlane_b32 s7, v130, 48
	s_nop 1
	v_mov_b32_e32 v131, s0
	v_add_f32_e32 v131, s1, v131
	v_add_f32_e32 v131, s6, v131
	v_add_f32_e32 v131, s7, v131
	v_fmamk_f32 v131, v131, 0x3a800000, v135
	v_rsq_f32_e32 v132, v131
	s_nop 0
	v_mul_f32_e32 v114, v18, v132
	v_mul_f32_e32 v115, v19, v132
	v_mul_f32_e32 v116, v20, v132
	v_mul_f32_e32 v117, v21, v132
	v_mul_f32_e32 v118, v22, v132
	v_mul_f32_e32 v119, v23, v132
	v_mul_f32_e32 v120, v24, v132
	v_mul_f32_e32 v121, v25, v132
	v_mul_f32_e32 v122, v26, v132
	v_mul_f32_e32 v123, v27, v132
	v_mul_f32_e32 v124, v28, v132
	v_mul_f32_e32 v125, v29, v132
	v_mul_f32_e32 v126, v30, v132
	v_mul_f32_e32 v127, v31, v132
	v_mul_f32_e32 v128, v32, v132
	v_mul_f32_e32 v129, v33, v132
	v_mul_f32_e32 v114, v66, v114
	v_mul_f32_e32 v115, v67, v115
	v_mul_f32_e32 v116, v68, v116
	v_mul_f32_e32 v117, v69, v117
	v_mul_f32_e32 v118, v70, v118
	v_mul_f32_e32 v119, v71, v119
	v_mul_f32_e32 v120, v72, v120
	v_mul_f32_e32 v121, v73, v121
	v_mul_f32_e32 v122, v74, v122
	v_mul_f32_e32 v123, v75, v123
	v_mul_f32_e32 v124, v76, v124
	v_mul_f32_e32 v125, v77, v125
	v_mul_f32_e32 v126, v78, v126
	v_mul_f32_e32 v127, v79, v127
	v_mul_f32_e32 v128, v80, v128
	v_mul_f32_e32 v129, v81, v129
	v_fma_f32 v114, v114, v98, v82
	v_fma_f32 v115, v115, v99, v83
	v_fma_f32 v116, v116, v100, v84
	v_fma_f32 v117, v117, v101, v85
	v_fma_f32 v118, v118, v102, v86
	v_fma_f32 v119, v119, v103, v87
	v_fma_f32 v120, v120, v104, v88
	v_fma_f32 v121, v121, v105, v89
	v_fma_f32 v122, v122, v106, v90
	v_fma_f32 v123, v123, v107, v91
	v_fma_f32 v124, v124, v108, v92
	v_fma_f32 v125, v125, v109, v93
	v_fma_f32 v126, v126, v110, v94
	v_fma_f32 v127, v127, v111, v95
	v_fma_f32 v128, v128, v112, v96
	v_fma_f32 v129, v129, v113, v97
	v_cvt_pk_bf16_f32 v114, v114, v115
	v_cvt_pk_bf16_f32 v115, v116, v117
	v_cvt_pk_bf16_f32 v116, v118, v119
	v_cvt_pk_bf16_f32 v117, v120, v121
	v_cvt_pk_bf16_f32 v118, v122, v123
	v_cvt_pk_bf16_f32 v119, v124, v125
	v_cvt_pk_bf16_f32 v120, v126, v127
	v_cvt_pk_bf16_f32 v121, v128, v129
	global_store_dwordx2 v134, v[114:115], s[38:39]
	global_store_dwordx2 v134, v[116:117], s[38:39] offset:512
	global_store_dwordx2 v134, v[118:119], s[38:39] offset:1024
	global_store_dwordx2 v134, v[120:121], s[38:39] offset:1536
	s_add_u32 s36, s36, 0x200000
	s_addc_u32 s37, s37, 0
	s_add_u32 s38, s38, 0x200000
	s_addc_u32 s39, s39, 0
	s_cmp_eq_u32 s8, 3
	s_cbranch_scc1 .Lnorm0_last
	s_add_u32 s10, s10, 0x400000
	s_addc_u32 s11, s11, 0
	s_add_u32 s12, s12, 0x400000
	s_addc_u32 s13, s13, 0
	global_load_dwordx4 v[2:5], v133, s[10:11] nt
	global_load_dwordx4 v[6:9], v133, s[10:11] offset:1024 nt
	global_load_dwordx4 v[10:13], v133, s[10:11] offset:2048 nt
	global_load_dwordx4 v[14:17], v133, s[10:11] offset:3072 nt
	global_load_dwordx4 v[18:21], v133, s[12:13] nt
	global_load_dwordx4 v[22:25], v133, s[12:13] offset:1024 nt
	global_load_dwordx4 v[26:29], v133, s[12:13] offset:2048 nt
	global_load_dwordx4 v[30:33], v133, s[12:13] offset:3072 nt
	s_waitcnt vmcnt(20)
	v_mul_f32_e32 v130, v34, v34
	v_fmac_f32_e32 v130, v35, v35
	v_fmac_f32_e32 v130, v36, v36
	v_fmac_f32_e32 v130, v37, v37
	v_fmac_f32_e32 v130, v38, v38
	v_fmac_f32_e32 v130, v39, v39
	v_fmac_f32_e32 v130, v40, v40
	v_fmac_f32_e32 v130, v41, v41
	v_fmac_f32_e32 v130, v42, v42
	v_fmac_f32_e32 v130, v43, v43
	v_fmac_f32_e32 v130, v44, v44
	v_fmac_f32_e32 v130, v45, v45
	v_fmac_f32_e32 v130, v46, v46
	v_fmac_f32_e32 v130, v47, v47
	v_fmac_f32_e32 v130, v48, v48
	v_fmac_f32_e32 v130, v49, v49
	s_nop 1
	v_add_f32_dpp v131, v130, v130 quad_perm:[1,0,3,2] row_mask:0xf bank_mask:0xf
	s_nop 1
	v_add_f32_dpp v130, v131, v131 quad_perm:[2,3,0,1] row_mask:0xf bank_mask:0xf
	s_nop 1
	v_add_f32_dpp v131, v130, v130 row_half_mirror row_mask:0xf bank_mask:0xf
	s_nop 1
	v_add_f32_dpp v130, v131, v131 row_mirror row_mask:0xf bank_mask:0xf
	s_nop 0
	v_readlane_b32 s0, v130, 0
	v_readlane_b32 s1, v130, 16
	v_readlane_b32 s6, v130, 32
	v_readlane_b32 s7, v130, 48
	s_nop 1
	v_mov_b32_e32 v131, s0
	v_add_f32_e32 v131, s1, v131
	v_add_f32_e32 v131, s6, v131
	v_add_f32_e32 v131, s7, v131
	v_fmamk_f32 v131, v131, 0x3a800000, v135
	v_rsq_f32_e32 v132, v131
	s_nop 0
	v_mul_f32_e32 v114, v34, v132
	v_mul_f32_e32 v115, v35, v132
	v_mul_f32_e32 v116, v36, v132
	v_mul_f32_e32 v117, v37, v132
	v_mul_f32_e32 v118, v38, v132
	v_mul_f32_e32 v119, v39, v132
	v_mul_f32_e32 v120, v40, v132
	v_mul_f32_e32 v121, v41, v132
	v_mul_f32_e32 v122, v42, v132
	v_mul_f32_e32 v123, v43, v132
	v_mul_f32_e32 v124, v44, v132
	v_mul_f32_e32 v125, v45, v132
	v_mul_f32_e32 v126, v46, v132
	v_mul_f32_e32 v127, v47, v132
	v_mul_f32_e32 v128, v48, v132
	v_mul_f32_e32 v129, v49, v132
	v_mul_f32_e32 v114, v66, v114
	v_mul_f32_e32 v115, v67, v115
	v_mul_f32_e32 v116, v68, v116
	v_mul_f32_e32 v117, v69, v117
	v_mul_f32_e32 v118, v70, v118
	v_mul_f32_e32 v119, v71, v119
	v_mul_f32_e32 v120, v72, v120
	v_mul_f32_e32 v121, v73, v121
	v_mul_f32_e32 v122, v74, v122
	v_mul_f32_e32 v123, v75, v123
	v_mul_f32_e32 v124, v76, v124
	v_mul_f32_e32 v125, v77, v125
	v_mul_f32_e32 v126, v78, v126
	v_mul_f32_e32 v127, v79, v127
	v_mul_f32_e32 v128, v80, v128
	v_mul_f32_e32 v129, v81, v129
	v_fma_f32 v114, v114, v98, v82
	v_fma_f32 v115, v115, v99, v83
	v_fma_f32 v116, v116, v100, v84
	v_fma_f32 v117, v117, v101, v85
	v_fma_f32 v118, v118, v102, v86
	v_fma_f32 v119, v119, v103, v87
	v_fma_f32 v120, v120, v104, v88
	v_fma_f32 v121, v121, v105, v89
	v_fma_f32 v122, v122, v106, v90
	v_fma_f32 v123, v123, v107, v91
	v_fma_f32 v124, v124, v108, v92
	v_fma_f32 v125, v125, v109, v93
	v_fma_f32 v126, v126, v110, v94
	v_fma_f32 v127, v127, v111, v95
	v_fma_f32 v128, v128, v112, v96
	v_fma_f32 v129, v129, v113, v97
	v_cvt_pk_bf16_f32 v114, v114, v115
	v_cvt_pk_bf16_f32 v115, v116, v117
	v_cvt_pk_bf16_f32 v116, v118, v119
	v_cvt_pk_bf16_f32 v117, v120, v121
	v_cvt_pk_bf16_f32 v118, v122, v123
	v_cvt_pk_bf16_f32 v119, v124, v125
	v_cvt_pk_bf16_f32 v120, v126, v127
	v_cvt_pk_bf16_f32 v121, v128, v129
	global_store_dwordx2 v134, v[114:115], s[36:37]
	global_store_dwordx2 v134, v[116:117], s[36:37] offset:512
	global_store_dwordx2 v134, v[118:119], s[36:37] offset:1024
	global_store_dwordx2 v134, v[120:121], s[36:37] offset:1536
	s_waitcnt vmcnt(12)
	v_mul_f32_e32 v130, v50, v50
	v_fmac_f32_e32 v130, v51, v51
	v_fmac_f32_e32 v130, v52, v52
	v_fmac_f32_e32 v130, v53, v53
	v_fmac_f32_e32 v130, v54, v54
	v_fmac_f32_e32 v130, v55, v55
	v_fmac_f32_e32 v130, v56, v56
	v_fmac_f32_e32 v130, v57, v57
	v_fmac_f32_e32 v130, v58, v58
	v_fmac_f32_e32 v130, v59, v59
	v_fmac_f32_e32 v130, v60, v60
	v_fmac_f32_e32 v130, v61, v61
	v_fmac_f32_e32 v130, v62, v62
	v_fmac_f32_e32 v130, v63, v63
	v_fmac_f32_e32 v130, v64, v64
	v_fmac_f32_e32 v130, v65, v65
	s_nop 1
	v_add_f32_dpp v131, v130, v130 quad_perm:[1,0,3,2] row_mask:0xf bank_mask:0xf
	s_nop 1
	v_add_f32_dpp v130, v131, v131 quad_perm:[2,3,0,1] row_mask:0xf bank_mask:0xf
	s_nop 1
	v_add_f32_dpp v131, v130, v130 row_half_mirror row_mask:0xf bank_mask:0xf
	s_nop 1
	v_add_f32_dpp v130, v131, v131 row_mirror row_mask:0xf bank_mask:0xf
	s_nop 0
	v_readlane_b32 s0, v130, 0
	v_readlane_b32 s1, v130, 16
	v_readlane_b32 s6, v130, 32
	v_readlane_b32 s7, v130, 48
	s_nop 1
	v_mov_b32_e32 v131, s0
	v_add_f32_e32 v131, s1, v131
	v_add_f32_e32 v131, s6, v131
	v_add_f32_e32 v131, s7, v131
	v_fmamk_f32 v131, v131, 0x3a800000, v135
	v_rsq_f32_e32 v132, v131
	s_nop 0
	v_mul_f32_e32 v114, v50, v132
	v_mul_f32_e32 v115, v51, v132
	v_mul_f32_e32 v116, v52, v132
	v_mul_f32_e32 v117, v53, v132
	v_mul_f32_e32 v118, v54, v132
	v_mul_f32_e32 v119, v55, v132
	v_mul_f32_e32 v120, v56, v132
	v_mul_f32_e32 v121, v57, v132
	v_mul_f32_e32 v122, v58, v132
	v_mul_f32_e32 v123, v59, v132
	v_mul_f32_e32 v124, v60, v132
	v_mul_f32_e32 v125, v61, v132
	v_mul_f32_e32 v126, v62, v132
	v_mul_f32_e32 v127, v63, v132
	v_mul_f32_e32 v128, v64, v132
	v_mul_f32_e32 v129, v65, v132
	v_mul_f32_e32 v114, v66, v114
	v_mul_f32_e32 v115, v67, v115
	v_mul_f32_e32 v116, v68, v116
	v_mul_f32_e32 v117, v69, v117
	v_mul_f32_e32 v118, v70, v118
	v_mul_f32_e32 v119, v71, v119
	v_mul_f32_e32 v120, v72, v120
	v_mul_f32_e32 v121, v73, v121
	v_mul_f32_e32 v122, v74, v122
	v_mul_f32_e32 v123, v75, v123
	v_mul_f32_e32 v124, v76, v124
	v_mul_f32_e32 v125, v77, v125
	v_mul_f32_e32 v126, v78, v126
	v_mul_f32_e32 v127, v79, v127
	v_mul_f32_e32 v128, v80, v128
	v_mul_f32_e32 v129, v81, v129
	v_fma_f32 v114, v114, v98, v82
	v_fma_f32 v115, v115, v99, v83
	v_fma_f32 v116, v116, v100, v84
	v_fma_f32 v117, v117, v101, v85
	v_fma_f32 v118, v118, v102, v86
	v_fma_f32 v119, v119, v103, v87
	v_fma_f32 v120, v120, v104, v88
	v_fma_f32 v121, v121, v105, v89
	v_fma_f32 v122, v122, v106, v90
	v_fma_f32 v123, v123, v107, v91
	v_fma_f32 v124, v124, v108, v92
	v_fma_f32 v125, v125, v109, v93
	v_fma_f32 v126, v126, v110, v94
	v_fma_f32 v127, v127, v111, v95
	v_fma_f32 v128, v128, v112, v96
	v_fma_f32 v129, v129, v113, v97
	v_cvt_pk_bf16_f32 v114, v114, v115
	v_cvt_pk_bf16_f32 v115, v116, v117
	v_cvt_pk_bf16_f32 v116, v118, v119
	v_cvt_pk_bf16_f32 v117, v120, v121
	v_cvt_pk_bf16_f32 v118, v122, v123
	v_cvt_pk_bf16_f32 v119, v124, v125
	v_cvt_pk_bf16_f32 v120, v126, v127
	v_cvt_pk_bf16_f32 v121, v128, v129
	global_store_dwordx2 v134, v[114:115], s[38:39]
	global_store_dwordx2 v134, v[116:117], s[38:39] offset:512
	global_store_dwordx2 v134, v[118:119], s[38:39] offset:1024
	global_store_dwordx2 v134, v[120:121], s[38:39] offset:1536
	s_add_u32 s36, s36, 0x200000
	s_addc_u32 s37, s37, 0
	s_add_u32 s38, s38, 0x200000
	s_addc_u32 s39, s39, 0
	s_add_u32 s8, s8, 1
	s_branch .Lnorm0_loop
.Lnorm0_last:
	s_waitcnt vmcnt(12)
	v_mul_f32_e32 v130, v34, v34
	v_fmac_f32_e32 v130, v35, v35
	v_fmac_f32_e32 v130, v36, v36
	v_fmac_f32_e32 v130, v37, v37
	v_fmac_f32_e32 v130, v38, v38
	v_fmac_f32_e32 v130, v39, v39
	v_fmac_f32_e32 v130, v40, v40
	v_fmac_f32_e32 v130, v41, v41
	v_fmac_f32_e32 v130, v42, v42
	v_fmac_f32_e32 v130, v43, v43
	v_fmac_f32_e32 v130, v44, v44
	v_fmac_f32_e32 v130, v45, v45
	v_fmac_f32_e32 v130, v46, v46
	v_fmac_f32_e32 v130, v47, v47
	v_fmac_f32_e32 v130, v48, v48
	v_fmac_f32_e32 v130, v49, v49
	s_nop 1
	v_add_f32_dpp v131, v130, v130 quad_perm:[1,0,3,2] row_mask:0xf bank_mask:0xf
	s_nop 1
	v_add_f32_dpp v130, v131, v131 quad_perm:[2,3,0,1] row_mask:0xf bank_mask:0xf
	s_nop 1
	v_add_f32_dpp v131, v130, v130 row_half_mirror row_mask:0xf bank_mask:0xf
	s_nop 1
	v_add_f32_dpp v130, v131, v131 row_mirror row_mask:0xf bank_mask:0xf
	s_nop 0
	v_readlane_b32 s0, v130, 0
	v_readlane_b32 s1, v130, 16
	v_readlane_b32 s6, v130, 32
	v_readlane_b32 s7, v130, 48
	s_nop 1
	v_mov_b32_e32 v131, s0
	v_add_f32_e32 v131, s1, v131
	v_add_f32_e32 v131, s6, v131
	v_add_f32_e32 v131, s7, v131
	v_fmamk_f32 v131, v131, 0x3a800000, v135
	v_rsq_f32_e32 v132, v131
	s_nop 0
	v_mul_f32_e32 v114, v34, v132
	v_mul_f32_e32 v115, v35, v132
	v_mul_f32_e32 v116, v36, v132
	v_mul_f32_e32 v117, v37, v132
	v_mul_f32_e32 v118, v38, v132
	v_mul_f32_e32 v119, v39, v132
	v_mul_f32_e32 v120, v40, v132
	v_mul_f32_e32 v121, v41, v132
	v_mul_f32_e32 v122, v42, v132
	v_mul_f32_e32 v123, v43, v132
	v_mul_f32_e32 v124, v44, v132
	v_mul_f32_e32 v125, v45, v132
	v_mul_f32_e32 v126, v46, v132
	v_mul_f32_e32 v127, v47, v132
	v_mul_f32_e32 v128, v48, v132
	v_mul_f32_e32 v129, v49, v132
	v_mul_f32_e32 v114, v66, v114
	v_mul_f32_e32 v115, v67, v115
	v_mul_f32_e32 v116, v68, v116
	v_mul_f32_e32 v117, v69, v117
	v_mul_f32_e32 v118, v70, v118
	v_mul_f32_e32 v119, v71, v119
	v_mul_f32_e32 v120, v72, v120
	v_mul_f32_e32 v121, v73, v121
	v_mul_f32_e32 v122, v74, v122
	v_mul_f32_e32 v123, v75, v123
	v_mul_f32_e32 v124, v76, v124
	v_mul_f32_e32 v125, v77, v125
	v_mul_f32_e32 v126, v78, v126
	v_mul_f32_e32 v127, v79, v127
	v_mul_f32_e32 v128, v80, v128
	v_mul_f32_e32 v129, v81, v129
	v_fma_f32 v114, v114, v98, v82
	v_fma_f32 v115, v115, v99, v83
	v_fma_f32 v116, v116, v100, v84
	v_fma_f32 v117, v117, v101, v85
	v_fma_f32 v118, v118, v102, v86
	v_fma_f32 v119, v119, v103, v87
	v_fma_f32 v120, v120, v104, v88
	v_fma_f32 v121, v121, v105, v89
	v_fma_f32 v122, v122, v106, v90
	v_fma_f32 v123, v123, v107, v91
	v_fma_f32 v124, v124, v108, v92
	v_fma_f32 v125, v125, v109, v93
	v_fma_f32 v126, v126, v110, v94
	v_fma_f32 v127, v127, v111, v95
	v_fma_f32 v128, v128, v112, v96
	v_fma_f32 v129, v129, v113, v97
	v_cvt_pk_bf16_f32 v114, v114, v115
	v_cvt_pk_bf16_f32 v115, v116, v117
	v_cvt_pk_bf16_f32 v116, v118, v119
	v_cvt_pk_bf16_f32 v117, v120, v121
	v_cvt_pk_bf16_f32 v118, v122, v123
	v_cvt_pk_bf16_f32 v119, v124, v125
	v_cvt_pk_bf16_f32 v120, v126, v127
	v_cvt_pk_bf16_f32 v121, v128, v129
	global_store_dwordx2 v134, v[114:115], s[36:37]
	global_store_dwordx2 v134, v[116:117], s[36:37] offset:512
	global_store_dwordx2 v134, v[118:119], s[36:37] offset:1024
	global_store_dwordx2 v134, v[120:121], s[36:37] offset:1536
	s_waitcnt vmcnt(4)
	v_mul_f32_e32 v130, v50, v50
	v_fmac_f32_e32 v130, v51, v51
	v_fmac_f32_e32 v130, v52, v52
	v_fmac_f32_e32 v130, v53, v53
	v_fmac_f32_e32 v130, v54, v54
	v_fmac_f32_e32 v130, v55, v55
	v_fmac_f32_e32 v130, v56, v56
	v_fmac_f32_e32 v130, v57, v57
	v_fmac_f32_e32 v130, v58, v58
	v_fmac_f32_e32 v130, v59, v59
	v_fmac_f32_e32 v130, v60, v60
	v_fmac_f32_e32 v130, v61, v61
	v_fmac_f32_e32 v130, v62, v62
	v_fmac_f32_e32 v130, v63, v63
	v_fmac_f32_e32 v130, v64, v64
	v_fmac_f32_e32 v130, v65, v65
	s_nop 1
	v_add_f32_dpp v131, v130, v130 quad_perm:[1,0,3,2] row_mask:0xf bank_mask:0xf
	s_nop 1
	v_add_f32_dpp v130, v131, v131 quad_perm:[2,3,0,1] row_mask:0xf bank_mask:0xf
	s_nop 1
	v_add_f32_dpp v131, v130, v130 row_half_mirror row_mask:0xf bank_mask:0xf
	s_nop 1
	v_add_f32_dpp v130, v131, v131 row_mirror row_mask:0xf bank_mask:0xf
	s_nop 0
	v_readlane_b32 s0, v130, 0
	v_readlane_b32 s1, v130, 16
	v_readlane_b32 s6, v130, 32
	v_readlane_b32 s7, v130, 48
	s_nop 1
	v_mov_b32_e32 v131, s0
	v_add_f32_e32 v131, s1, v131
	v_add_f32_e32 v131, s6, v131
	v_add_f32_e32 v131, s7, v131
	v_fmamk_f32 v131, v131, 0x3a800000, v135
	v_rsq_f32_e32 v132, v131
	s_nop 0
	v_mul_f32_e32 v114, v50, v132
	v_mul_f32_e32 v115, v51, v132
	v_mul_f32_e32 v116, v52, v132
	v_mul_f32_e32 v117, v53, v132
	v_mul_f32_e32 v118, v54, v132
	v_mul_f32_e32 v119, v55, v132
	v_mul_f32_e32 v120, v56, v132
	v_mul_f32_e32 v121, v57, v132
	v_mul_f32_e32 v122, v58, v132
	v_mul_f32_e32 v123, v59, v132
	v_mul_f32_e32 v124, v60, v132
	v_mul_f32_e32 v125, v61, v132
	v_mul_f32_e32 v126, v62, v132
	v_mul_f32_e32 v127, v63, v132
	v_mul_f32_e32 v128, v64, v132
	v_mul_f32_e32 v129, v65, v132
	v_mul_f32_e32 v114, v66, v114
	v_mul_f32_e32 v115, v67, v115
	v_mul_f32_e32 v116, v68, v116
	v_mul_f32_e32 v117, v69, v117
	v_mul_f32_e32 v118, v70, v118
	v_mul_f32_e32 v119, v71, v119
	v_mul_f32_e32 v120, v72, v120
	v_mul_f32_e32 v121, v73, v121
	v_mul_f32_e32 v122, v74, v122
	v_mul_f32_e32 v123, v75, v123
	v_mul_f32_e32 v124, v76, v124
	v_mul_f32_e32 v125, v77, v125
	v_mul_f32_e32 v126, v78, v126
	v_mul_f32_e32 v127, v79, v127
	v_mul_f32_e32 v128, v80, v128
	v_mul_f32_e32 v129, v81, v129
	v_fma_f32 v114, v114, v98, v82
	v_fma_f32 v115, v115, v99, v83
	v_fma_f32 v116, v116, v100, v84
	v_fma_f32 v117, v117, v101, v85
	v_fma_f32 v118, v118, v102, v86
	v_fma_f32 v119, v119, v103, v87
	v_fma_f32 v120, v120, v104, v88
	v_fma_f32 v121, v121, v105, v89
	v_fma_f32 v122, v122, v106, v90
	v_fma_f32 v123, v123, v107, v91
	v_fma_f32 v124, v124, v108, v92
	v_fma_f32 v125, v125, v109, v93
	v_fma_f32 v126, v126, v110, v94
	v_fma_f32 v127, v127, v111, v95
	v_fma_f32 v128, v128, v112, v96
	v_fma_f32 v129, v129, v113, v97
	v_cvt_pk_bf16_f32 v114, v114, v115
	v_cvt_pk_bf16_f32 v115, v116, v117
	v_cvt_pk_bf16_f32 v116, v118, v119
	v_cvt_pk_bf16_f32 v117, v120, v121
	v_cvt_pk_bf16_f32 v118, v122, v123
	v_cvt_pk_bf16_f32 v119, v124, v125
	v_cvt_pk_bf16_f32 v120, v126, v127
	v_cvt_pk_bf16_f32 v121, v128, v129
	global_store_dwordx2 v134, v[114:115], s[38:39]
	global_store_dwordx2 v134, v[116:117], s[38:39] offset:512
	global_store_dwordx2 v134, v[118:119], s[38:39] offset:1024
	global_store_dwordx2 v134, v[120:121], s[38:39] offset:1536
	s_add_u32 s36, s36, 0x200000
	s_addc_u32 s37, s37, 0
	s_add_u32 s38, s38, 0x200000
	s_addc_u32 s39, s39, 0
	s_branch .LBB0_42
.Lnorm0_orig:
	v_lshlrev_b32_e32 v30, 2, v2
	v_mbcnt_hi_u32_b32 v2, -1, v139
	v_and_b32_e32 v3, 64, v2
	v_add_u32_e32 v3, 64, v3
	v_xor_b32_e32 v4, 32, v2
	v_cmp_lt_i32_e32 vcc, v4, v3
	s_ashr_i32 s27, s26, 31
	s_lshl_b32 s0, s33, 4
	v_cndmask_b32_e32 v4, v2, v4, vcc
	v_lshlrev_b32_e32 v40, 2, v4
	v_xor_b32_e32 v4, 16, v2
	v_cmp_lt_i32_e32 vcc, v4, v3
	v_readlane_b32 s36, v255, 3
	s_lshl_b64 s[6:7], s[26:27], 12
	v_cndmask_b32_e32 v4, v2, v4, vcc
	v_lshlrev_b32_e32 v41, 2, v4
	v_xor_b32_e32 v4, 8, v2
	v_cmp_lt_i32_e32 vcc, v4, v3
	v_ashrrev_i32_e32 v31, 31, v30
	v_readlane_b32 s37, v255, 4
	v_cndmask_b32_e32 v4, v2, v4, vcc
	v_lshlrev_b32_e32 v42, 2, v4
	v_xor_b32_e32 v4, 4, v2
	v_cmp_lt_i32_e32 vcc, v4, v3
	s_add_u32 s6, s36, s6
	v_readlane_b32 s44, v255, 11
	v_cndmask_b32_e32 v4, v2, v4, vcc
	v_lshlrev_b32_e32 v43, 2, v4
	v_xor_b32_e32 v4, 2, v2
	v_cmp_lt_i32_e32 vcc, v4, v3
	v_readlane_b32 s45, v255, 12
	s_addc_u32 s7, s37, s7
	v_cndmask_b32_e32 v4, v2, v4, vcc
	v_lshlrev_b32_e32 v44, 2, v4
	v_xor_b32_e32 v4, 1, v2
	v_cmp_lt_i32_e32 vcc, v4, v3
	s_add_i32 s8, s26, s82
	s_ashr_i32 s1, s0, 31
	v_cndmask_b32_e32 v2, v2, v4, vcc
	v_lshlrev_b32_e32 v45, 2, v2
	v_lshlrev_b64 v[2:3], 2, v[30:31]
	v_lshl_add_u64 v[32:33], s[36:37], 0, v[2:3]
	v_lshl_add_u64 v[34:35], s[44:45], 0, v[2:3]
	v_lshl_add_u64 v[2:3], s[6:7], 0, v[2:3]
	s_mov_b64 s[6:7], 0x800
	s_ashr_i32 s9, s8, 31
	v_lshl_add_u64 v[36:37], v[2:3], 0, s[6:7]
	s_lshl_b64 s[6:7], s[0:1], 12
	s_lshl_b64 s[8:9], s[8:9], 11
	s_add_u32 s8, s60, s8
	s_addc_u32 s9, s61, s9
	s_lshl_b64 s[10:11], s[0:1], 11
	s_lshl_b64 s[12:13], s[26:27], 11
	s_add_u32 s12, s60, s12
	v_lshlrev_b64 v[38:39], 1, v[30:31]
	s_addc_u32 s13, s61, s13
	v_mov_b32_e32 v46, 0x358637bd
	s_mov_b32 s1, 0x800000
	s_mov_b64 s[28:29], 0x1000
	s_movk_i32 s3, 0x1000
	s_mov_b32 s27, s26
	v_readlane_b32 s38, v255, 5
	v_readlane_b32 s39, v255, 6
	v_readlane_b32 s40, v255, 7
	v_readlane_b32 s41, v255, 8
	v_readlane_b32 s42, v255, 9
	v_readlane_b32 s43, v255, 10
	v_readlane_b32 s46, v255, 13
	v_readlane_b32 s47, v255, 14
	v_readlane_b32 s48, v255, 15
	v_readlane_b32 s49, v255, 16
	v_readlane_b32 s50, v255, 17
	v_readlane_b32 s51, v255, 18
	s_branch .LBB0_40
